# mirrored the row-tile order of every big GEMM except the value-half up-projection so each phase first touches the rows its producer wrote last (last-level-cache reuse between consecutive phases)
# speedup vs baseline: 1.0092x; 1.0047x over previous
;     __host__ __device__ bool next(int i, Unit& u) const {
;         const long L = (long)i * G + c; if (L >= nwg) return false;
;         int wgid = (int)L; { const int q = nwg / NXCD, r = nwg % NXCD, xcd = wgid % NXCD, off = wgid / NXCD; wgid = (xcd < r ? xcd * (q + 1) : r * (q + 1) + (xcd - r) * q) + off; }
;         const int nig = WGM * nN, gid = wgid / nig, fm = gid * WGM, gsz = (nM - fm) < WGM ? (nM - fm) : WGM;
;         u.pm = fm + ((wgid % nig) % gsz); u.pn = (wgid % nig) / gsz; return true;
; template <class Epi, class Sched, bool STAMP = false>
; __device__ __forceinline__ void gemm_phase(PG8_LAS unsigned char* lds, const Gemm g, const Sched& S, const Epi& E, unsigned long long* stamps) {
;     ...
;     if (!S.next(0, cur)) return;
.LBB0_731:
	s_lshr_b32 s73, s68, 5
	v_cvt_f32_u32_e32 v2, s73
	v_mov_b32_e32 v9, v169
	s_cmp_lt_i32 s2, s68
	s_cselect_b64 s[0:1], -1, 0
	s_cmp_ge_i32 s2, s68
	v_readfirstlane_b32 s76, v9
	s_cbranch_scc1 .LBB0_733
	v_rcp_iflag_f32_e32 v1, v2
	s_lshr_b32 s5, s68, 3
	v_readlane_b32 s20, v237, 32
	s_or_b32 s5, s5, s20
	v_mul_f32_e32 v1, 0x4f7ffffe, v1
	v_cvt_u32_f32_e32 v1, v1
	v_readlane_b32 s20, v237, 31
	s_sub_i32 s22, 0, s73
	s_mul_i32 s5, s5, s20
	v_readfirstlane_b32 s23, v1
	v_readlane_b32 s20, v237, 24
	s_mul_i32 s22, s22, s23
	s_add_i32 s5, s5, s20
	s_mul_hi_u32 s22, s23, s22
	s_abs_i32 s21, s5
	s_add_i32 s23, s23, s22
	s_mul_hi_u32 s22, s21, s23
	s_mul_i32 s23, s22, s73
	s_sub_i32 s21, s21, s23
	s_ashr_i32 s20, s5, 31
	s_add_i32 s23, s22, 1
	s_sub_i32 s26, s21, s73
	s_cmp_ge_u32 s21, s73
	s_cselect_b32 s22, s23, s22
	s_cselect_b32 s21, s26, s21
	s_add_i32 s23, s22, 1
	s_cmp_ge_u32 s21, s73
	s_cselect_b32 s21, s23, s22
	s_xor_b32 s21, s21, s20
	s_sub_i32 s20, s21, s20
	s_lshl_b32 s22, s20, 3
	s_sub_i32 s21, 0x100, s22
	s_min_i32 s23, s21, 8
	s_sext_i32_i16 s21, s23
	v_cvt_f32_i32_e32 v1, s21
	s_mul_i32 s20, s20, s73
	s_sub_i32 s5, s5, s20
	s_sext_i32_i16 s20, s5
	v_cvt_f32_i32_e32 v3, s20
	v_rcp_iflag_f32_e32 v4, v1
	s_xor_b32 s20, s20, s21
	s_ashr_i32 s20, s20, 30
	s_or_b32 s26, s20, 1
	v_mul_f32_e32 v4, v3, v4
	v_trunc_f32_e32 v4, v4
	v_fma_f32 v3, -v4, v1, v3
	v_cvt_i32_f32_e32 v4, v4
	v_cmp_ge_f32_e64 s[20:21], |v3|, |v1|
	s_and_b64 s[20:21], s[20:21], exec
	s_cselect_b32 s20, s26, 0
	v_readfirstlane_b32 s21, v4
	s_add_i32 s20, s21, s20
	s_sext_i32_i16 s97, s20
	s_mul_i32 s20, s20, s23
	s_sub_i32 s5, s5, s20
	s_sext_i32_i16 s5, s5
	s_add_i32 s75, s22, s5
	s_sub_i32 s98, 0xff, s75
	s_cmp_eq_u32 s77, 3
	s_cselect_b32 s75, s75, s98

;     __host__ __device__ bool next(int i, Unit& u) const {
;         const long L = (long)i * G + c; if (L >= nwg) return false;
;         int wgid = (int)L; { const int q = nwg / NXCD, r = nwg % NXCD, xcd = wgid % NXCD, off = wgid / NXCD; wgid = (xcd < r ? xcd * (q + 1) : r * (q + 1) + (xcd - r) * q) + off; }
;         const int nig = WGM * nN, gid = wgid / nig, fm = gid * WGM, gsz = (nM - fm) < WGM ? (nM - fm) : WGM;
;         u.pm = fm + ((wgid % nig) % gsz); u.pn = (wgid % nig) / gsz; return true;
; template <class Epi, class Sched, bool STAMP = false>
; __device__ __forceinline__ void gemm_phase(PG8_LAS unsigned char* lds, const Gemm g, const Sched& S, const Epi& E, unsigned long long* stamps) {
;     ...
;         const bool has_next = S.next(ui + 1, nxt);
.LBB0_738:
	s_add_i32 s70, s70, 1
	s_mul_i32 s0, s70, s17
	s_mul_hi_u32 s1, s70, s96
	s_add_i32 s1, s1, s0
	s_mul_i32 s0, s70, s96
	s_add_u32 s30, s0, s2
	s_addc_u32 s31, s1, s13
	v_mov_b64_e32 v[2:3], s[68:69]
	v_cmp_ge_i64_e64 s[36:37], s[30:31], v[2:3]
	v_cmp_lt_i64_e64 s[0:1], s[30:31], v[2:3]
	s_and_b64 vcc, exec, s[36:37]
	s_cbranch_vccnz .LBB0_740
	s_ashr_i32 s31, s30, 31
	s_lshr_b32 s31, s31, 29
	s_add_i32 s31, s30, s31
	s_ashr_i32 s38, s31, 3
	s_and_b32 s31, s31, -8
	s_sub_i32 s30, s30, s31
	s_lshr_b32 s31, s30, 31
	s_or_b32 s31, s31, s34
	s_mul_i32 s30, s31, s30
	s_add_i32 s30, s30, s38
	s_abs_i32 s38, s30
	s_mul_hi_u32 s39, s38, s71
	s_mul_i32 s62, s39, s73
	s_sub_i32 s38, s38, s62
	s_ashr_i32 s31, s30, 31
	s_add_i32 s62, s39, 1
	s_sub_i32 s63, s38, s73
	s_cmp_ge_u32 s38, s73
	s_cselect_b32 s39, s62, s39
	s_cselect_b32 s38, s63, s38
	s_add_i32 s62, s39, 1
	s_cmp_ge_u32 s38, s73
	s_cselect_b32 s38, s62, s39
	s_xor_b32 s38, s38, s31
	s_sub_i32 s31, s38, s31
	s_lshl_b32 s38, s31, 3
	s_sub_i32 s39, 0x100, s38
	s_min_i32 s39, s39, 8
	s_abs_i32 s62, s39
	v_cvt_f32_u32_e32 v2, s62
	s_sub_i32 s64, 0, s62
	s_mul_i32 s31, s31, s73
	s_sub_i32 s30, s30, s31
	v_rcp_iflag_f32_e32 v2, v2
	s_abs_i32 s63, s30
	s_xor_b32 s31, s30, s39
	s_ashr_i32 s31, s31, 31
	v_mul_f32_e32 v2, 0x4f7ffffe, v2
	v_cvt_u32_f32_e32 v2, v2
	s_nop 0
	v_readfirstlane_b32 s65, v2
	s_mul_i32 s64, s64, s65
	s_mul_hi_u32 s64, s65, s64
	s_add_i32 s65, s65, s64
	s_mul_hi_u32 s64, s63, s65
	s_mul_i32 s65, s64, s62
	s_sub_i32 s63, s63, s65
	s_add_i32 s65, s64, 1
	s_sub_i32 s74, s63, s62
	s_cmp_ge_u32 s63, s62
	s_cselect_b32 s64, s65, s64
	s_cselect_b32 s63, s74, s63
	s_add_i32 s65, s64, 1
	s_cmp_ge_u32 s63, s62
	s_cselect_b32 s62, s65, s64
	s_xor_b32 s62, s62, s31
	s_sub_i32 s92, s62, s31
	s_mul_i32 s31, s92, s39
	s_sub_i32 s30, s30, s31
	s_add_i32 s74, s30, s38
	s_sub_i32 s98, 0xff, s74
	s_cmp_eq_u32 s77, 3
	s_cselect_b32 s74, s74, s98
